# combo: sel LDS-read software pipelining + split read2 + list-chain counted waits, P1 gain-load batching, GEMM no-op setprio/wait removal
# speedup vs baseline: 1.0013x; 1.0013x over previous
; __global__ void __launch_bounds__(512, 2) mk_fwd(Args a) {
;     ...
;                 { TID_LOCALS
;                   const int mycnt = (int)CNT[l * 512 + tid];
;                   int v = (mycnt + 255) >> 8;
; #pragma unroll
;                   for (int o = 1; o < 64; o <<= 1) { const int t = __shfl_up(v, o); if (lane >= o) v += t; }
;                   if (lane == 63) wtot[wave] = v;
;                   __syncthreads();
;                   int add = 0;
; #pragma unroll
;                   for (int w = 0; w < 8; ++w) add += (w < wave) ? wtot[w] : 0;
;                   pre[tid] = v + add;
;                   __syncthreads(); }
.LBB0_31:
	s_andn2_b64 vcc, exec, s[0:1]
	s_cbranch_vccnz .LBB0_78
	v_mov_b32_e32 v0, v232
	s_waitcnt lgkmcnt(0)
	v_ashrrev_i32_e32 v1, 31, v0
	v_lshl_add_u64 v[2:3], v[0:1], 2, s[12:13]
	flat_load_dword v1, v[2:3]
	v_add_u32_e32 v3, -1, v237
	v_and_b32_e32 v4, 63, v0
	v_readfirstlane_b32 s0, v0
	s_ashr_i32 s6, s0, 6
	s_waitcnt vmcnt(0) lgkmcnt(0)
	v_lshlrev_b32_e32 v5, 2, v0
	v_add_u32_e32 v5, 0x23000, v5
	ds_write_b32 v5, v1
	v_add_u32_e32 v1, 0xff, v1
	v_ashrrev_i32_e32 v2, 8, v1
	v_and_b32_e32 v1, 64, v237
	v_cmp_lt_i32_e32 vcc, v3, v1
	s_nop 1
	v_cndmask_b32_e32 v3, v3, v237, vcc
	v_lshlrev_b32_e32 v3, 2, v3
	ds_bpermute_b32 v3, v3, v2
	v_cmp_ne_u32_e32 vcc, 0, v4
	s_waitcnt lgkmcnt(0)
	s_nop 0
	v_cndmask_b32_e32 v3, 0, v3, vcc
	v_add_u32_e32 v2, v3, v2
	v_add_u32_e32 v3, -2, v237
	v_cmp_lt_i32_e32 vcc, v3, v1
	s_nop 1
	v_cndmask_b32_e32 v3, v3, v237, vcc
	v_lshlrev_b32_e32 v3, 2, v3
	ds_bpermute_b32 v3, v3, v2
	v_cmp_lt_u32_e32 vcc, 1, v4
	s_waitcnt lgkmcnt(0)
	s_nop 0
	v_cndmask_b32_e32 v3, 0, v3, vcc
	v_add_u32_e32 v2, v3, v2
	v_add_u32_e32 v3, -4, v237
	v_cmp_lt_i32_e32 vcc, v3, v1
	s_nop 1
	v_cndmask_b32_e32 v3, v3, v237, vcc
	v_lshlrev_b32_e32 v3, 2, v3
	ds_bpermute_b32 v3, v3, v2
	v_cmp_lt_u32_e32 vcc, 3, v4
	s_waitcnt lgkmcnt(0)
	s_nop 0
	v_cndmask_b32_e32 v3, 0, v3, vcc
	v_add_u32_e32 v2, v3, v2
	v_add_u32_e32 v3, -8, v237
	v_cmp_lt_i32_e32 vcc, v3, v1
	s_nop 1
	v_cndmask_b32_e32 v3, v3, v237, vcc
	v_lshlrev_b32_e32 v3, 2, v3
	ds_bpermute_b32 v3, v3, v2
	v_cmp_lt_u32_e32 vcc, 7, v4
	s_waitcnt lgkmcnt(0)
	s_nop 0
	v_cndmask_b32_e32 v3, 0, v3, vcc
	v_add_u32_e32 v2, v3, v2
	v_add_u32_e32 v3, -16, v237
	v_cmp_lt_i32_e32 vcc, v3, v1
	s_nop 1
	v_cndmask_b32_e32 v3, v3, v237, vcc
	v_lshlrev_b32_e32 v3, 2, v3
	ds_bpermute_b32 v3, v3, v2
	v_cmp_lt_u32_e32 vcc, 15, v4
	s_waitcnt lgkmcnt(0)
	s_nop 0
	v_cndmask_b32_e32 v3, 0, v3, vcc
	v_add_u32_e32 v2, v3, v2
	v_subrev_u32_e32 v3, 32, v237
	v_cmp_lt_i32_e32 vcc, v3, v1
	s_nop 1
	v_cndmask_b32_e32 v3, v3, v237, vcc
	v_lshlrev_b32_e32 v3, 2, v3
	ds_bpermute_b32 v3, v3, v2
	v_cmp_lt_u32_e32 vcc, 31, v4
	s_waitcnt lgkmcnt(0)
	s_nop 0
	v_cndmask_b32_e32 v3, 0, v3, vcc
	v_add_u32_e32 v2, v3, v2
	v_cmp_eq_u32_e32 vcc, 63, v4
	s_and_saveexec_b64 s[0:1], vcc
	s_lshl_b32 s7, s6, 2
	s_add_i32 s7, s7, 0
	s_add_i32 s7, s7, 0x22800
	v_mov_b32_e32 v3, s7
	ds_write_b32 v3, v2
	s_or_b64 exec, exec, s[0:1]
	s_cmp_gt_i32 s6, 0
	v_mov_b32_e32 v3, 0
	v_mov_b32_e32 v4, 0
	s_waitcnt lgkmcnt(0)
	s_barrier
	s_cbranch_scc0 .LBB0_36
	s_add_i32 s0, 0, 0x22800
	v_mov_b32_e32 v4, s0
	ds_read_b32 v4, v4

; __device__ __forceinline__ void stage_kv_load(u32x4 (&kr)[8], u32x4 (&vr)[8], const bf16_t* Kg, int kpitch, const bf16_t* Vtg, int tid) {
; #pragma unroll
;     for (int i = 0; i < 8; ++i) { const int c = tid + 512 * i, row = c >> 4, ch = c & 15; kr[i] = *(const u32x4*)(Kg + (size_t)row * kpitch + ch * 8); }
; #pragma unroll
;     for (int i = 0; i < 8; ++i) { const int c = tid + 512 * i, row = c >> 5, ch = c & 31; vr[i] = *(const u32x4*)(Vtg + (size_t)row * 256 + ch * 8); }
; __global__ void __launch_bounds__(512, 2) mk_fwd(Args a) {
;     ...
;                     int lo = 0, hh = 511;
;                     while (lo < hh) { const int mid = (lo + hh) >> 1; if (pre[mid] > it) hh = mid; else lo = mid + 1; }
;                     const int p = lo, chunk = it - (p ? pre[p - 1] : 0), h = p >> 6, b = p & 63;
;                     const int pc = (int)CNT[l * 512 + p];
;                     const int e = chunk * 256 + 32 * wave + r32; const bool valid = e < pc;
;                     const unsigned ent = LIST[(size_t)p * SEQ + (valid ? e : 0)];
;                     u32x4 kr[8], vr[8];
;                     stage_kv_load(kr, vr, PROJ + (size_t)(256 * b) * INW + 1024 + 128 * h, INW, VT + (size_t)(h * 64 + b) * 128 * 256, tid);
;                     const int tok = (int)(ent >> 2), slot = (int)(ent & 3u);
;                     const bf16_t* qrow = PROJ + (size_t)tok * INW + 128 * h + 8 * hi;
;                     bf16x8 qf[8];
; #pragma unroll
;                     for (int d0 = 0; d0 < 8; ++d0) qf[d0] = *(const bf16x8*)(qrow + 16 * d0);
.LBB0_51:
	s_ashr_i32 s7, s6, 31
	s_lshr_b32 s28, s6, 6
	s_and_b32 s18, s6, 63
	s_lshl_b64 s[16:17], s[6:7], 2
	v_mov_b32_e32 v2, s16
	v_add_u32_e32 v2, 0x23000, v2
	ds_read_b32 v12, v2
	s_mov_b32 s7, s75
	s_ashr_i32 s15, s15, 1
	s_lshl_b64 s[6:7], s[6:7], 16
	s_andn2_b32 s15, s15, 31
	s_waitcnt lgkmcnt(0)
	v_sub_u32_e32 v1, s14, v1
	s_add_u32 s16, s58, s6
	v_lshlrev_b32_e32 v1, 8, v1
	s_mul_i32 s18, s18, 0x280000
	s_addc_u32 s17, s59, s7
	v_add_u32_e32 v1, s15, v1
	s_add_u32 s15, s72, s18
	s_addc_u32 s19, s73, 0
	s_lshl_b32 s74, s28, 8
	v_lshlrev_b32_e32 v2, 4, v0
	s_add_u32 s18, s15, s74
	v_mov_b32_e32 v67, v129
	v_add_u32_e32 v3, 0x200, v0
	v_add_u32_e32 v4, 0x400, v0
	v_add_u32_e32 v6, 0x800, v0
	v_add_u32_e32 v7, 0xa00, v0
	v_and_b32_e32 v66, 0xf0, v2
	s_addc_u32 s19, s19, 0
	v_and_b32_e32 v163, 31, v0
	v_ashrrev_i32_e32 v88, 4, v0
	v_add_u32_e32 v8, 0xc00, v0
	v_add_u32_e32 v9, 0xe00, v0
	v_ashrrev_i32_e32 v90, 4, v3
	v_ashrrev_i32_e32 v92, 4, v4
	v_ashrrev_i32_e32 v96, 4, v6
	v_ashrrev_i32_e32 v98, 4, v7
	v_ashrrev_i32_e32 v78, 5, v6
	v_ashrrev_i32_e32 v80, 5, v7
	s_add_u32 s22, s96, s6
	v_lshl_add_u64 v[6:7], s[18:19], 0, v[66:67]
	s_movk_i32 s18, 0x2800
	v_ashrrev_i32_e32 v100, 4, v8
	v_ashrrev_i32_e32 v102, 4, v9
	v_and_b32_e32 v68, 0x1f0, v2
	v_ashrrev_i32_e32 v72, 5, v3
	v_ashrrev_i32_e32 v82, 5, v8
	v_ashrrev_i32_e32 v84, 5, v9
	v_or_b32_e32 v1, v1, v163
	s_addc_u32 s23, s97, s7
	v_mad_i64_i32 v[2:3], s[6:7], v88, s18, v[6:7]
	v_mad_i64_i32 v[8:9], s[6:7], v90, s18, v[6:7]
	v_mad_i64_i32 v[10:11], s[6:7], v92, s18, v[6:7]
	v_add_u32_e32 v5, 0x600, v0
	v_ashrrev_i32_e32 v70, 5, v0
	v_ashrrev_i32_e32 v74, 5, v4
	v_ashrrev_i32_e32 v76, 5, v5
	v_bfe_u32 v167, v0, 5, 1
	v_mov_b32_e32 v69, v129
	v_ashrrev_i32_e32 v71, 31, v70
	v_ashrrev_i32_e32 v73, 31, v72
	v_ashrrev_i32_e32 v75, 31, v74
	v_ashrrev_i32_e32 v77, 31, v76
	v_ashrrev_i32_e32 v79, 31, v78
	v_ashrrev_i32_e32 v81, 31, v80
	v_ashrrev_i32_e32 v83, 31, v82
	v_ashrrev_i32_e32 v85, 31, v84
	v_ashrrev_i32_e32 v94, 4, v5
	v_lshlrev_b64 v[34:35], 9, v[70:71]
	v_lshlrev_b64 v[36:37], 9, v[72:73]
	v_lshlrev_b64 v[38:39], 9, v[74:75]
	v_lshl_add_u64 v[62:63], s[22:23], 0, v[68:69]
	v_lshlrev_b64 v[46:47], 9, v[76:77]
	v_lshlrev_b64 v[50:51], 9, v[78:79]
	v_lshlrev_b64 v[54:55], 9, v[80:81]
	v_lshlrev_b64 v[58:59], 9, v[82:83]
	v_lshlrev_b64 v[64:65], 9, v[84:85]
	v_mov_b32_e32 v87, v129
	v_lshlrev_b32_e32 v86, 4, v167
	v_lshl_add_u64 v[34:35], v[62:63], 0, v[34:35]
	v_lshl_add_u64 v[40:41], v[62:63], 0, v[36:37]
	v_lshl_add_u64 v[42:43], v[62:63], 0, v[38:39]
	v_lshl_add_u64 v[46:47], v[62:63], 0, v[46:47]
	v_cmp_lt_i32_e64 s[6:7], v1, v12
	v_lshl_add_u64 v[50:51], v[62:63], 0, v[50:51]
	v_lshl_add_u64 v[54:55], v[62:63], 0, v[54:55]
	v_cndmask_b32_e64 v12, 0, v1, s[6:7]
	v_ashrrev_i32_e32 v13, 31, v12
	v_lshl_add_u64 v[12:13], v[12:13], 2, s[16:17]
	global_load_dword v168, v[12:13], off
	v_mov_b64_e32 v[0:1], s[72:73]
	v_mad_i64_i32 v[14:15], s[16:17], v94, s18, v[6:7]
	v_mad_i64_i32 v[18:19], s[16:17], v96, s18, v[6:7]
	v_mad_i64_i32 v[22:23], s[16:17], v98, s18, v[6:7]
	v_mad_i64_i32 v[26:27], s[16:17], v100, s18, v[6:7]
	v_mad_i64_i32 v[30:31], s[16:17], v102, s18, v[6:7]
	v_lshl_add_u64 v[58:59], v[62:63], 0, v[58:59]
	v_lshl_add_u64 v[62:63], v[62:63], 0, v[64:65]
	global_load_dwordx4 v[2:5], v[2:3], off offset:2048
	s_nop 0
	global_load_dwordx4 v[6:9], v[8:9], off offset:2048
	s_nop 0
	global_load_dwordx4 v[10:13], v[10:11], off offset:2048
	s_nop 0
	global_load_dwordx4 v[14:17], v[14:15], off offset:2048
	s_nop 0
	global_load_dwordx4 v[18:21], v[18:19], off offset:2048
	s_nop 0
	global_load_dwordx4 v[22:25], v[22:23], off offset:2048
	s_nop 0
	global_load_dwordx4 v[26:29], v[26:27], off offset:2048
	s_nop 0
	global_load_dwordx4 v[30:33], v[30:31], off offset:2048
	s_nop 0
	global_load_dwordx4 v[34:37], v[34:35], off
	s_nop 0
	global_load_dwordx4 v[38:41], v[40:41], off
	s_nop 0
	global_load_dwordx4 v[42:45], v[42:43], off
	v_readlane_b32 s19, v254, 28
	global_load_dwordx4 v[46:49], v[46:47], off
	v_add_u32_e32 v66, 0, v66
	global_load_dwordx4 v[50:53], v[50:51], off
	v_add_u32_e32 v68, s19, v68
	global_load_dwordx4 v[54:57], v[54:55], off
	s_movk_i32 s20, 0x210
	global_load_dwordx4 v[58:61], v[58:59], off
	v_mad_u64_u32 v[88:89], s[16:17], v88, s86, v[66:67]
	global_load_dwordx4 v[62:65], v[62:63], off
	v_mad_u64_u32 v[90:91], s[16:17], v90, s86, v[66:67]
	v_mad_u64_u32 v[92:93], s[16:17], v92, s86, v[66:67]
	v_mad_u64_u32 v[94:95], s[16:17], v94, s86, v[66:67]
	v_mad_u64_u32 v[96:97], s[16:17], v96, s86, v[66:67]
	v_mad_u64_u32 v[98:99], s[16:17], v98, s86, v[66:67]
	v_mad_u64_u32 v[100:101], s[16:17], v100, s86, v[66:67]
	v_mad_u64_u32 v[66:67], s[16:17], v102, s86, v[66:67]
	v_mad_u64_u32 v[70:71], s[16:17], v70, s20, v[68:69]
	v_mad_u64_u32 v[72:73], s[16:17], v72, s20, v[68:69]
	v_mad_u64_u32 v[74:75], s[16:17], v74, s20, v[68:69]
	v_lshlrev_b32_e32 v164, 3, v167
	s_mov_b32 s15, 0
	v_add_u32_e32 v169, 0, v86
	s_mov_b64 s[60:61], -1
	v_mov_b32_e32 v162, 0xf149f2ca
	s_waitcnt vmcnt(16)
	v_lshrrev_b32_e32 v128, 2, v168
	v_mad_u64_u32 v[0:1], s[16:17], v128, s18, v[0:1]
	v_lshl_add_u64 v[0:1], v[0:1], 0, s[74:75]
	v_lshl_add_u64 v[0:1], v[0:1], 0, v[86:87]
	global_load_dwordx4 v[130:133], v[0:1], off
	global_load_dwordx4 v[134:137], v[0:1], off offset:32
	global_load_dwordx4 v[138:141], v[0:1], off offset:64
	global_load_dwordx4 v[142:145], v[0:1], off offset:96
	global_load_dwordx4 v[146:149], v[0:1], off offset:128
	global_load_dwordx4 v[150:153], v[0:1], off offset:160
	global_load_dwordx4 v[154:157], v[0:1], off offset:192
	global_load_dwordx4 v[158:161], v[0:1], off offset:224
	v_mad_u64_u32 v[0:1], s[16:17], v76, s20, v[68:69]
	s_waitcnt vmcnt(8) lgkmcnt(0)
; #define LAS __attribute__((address_space(3)))
; #define MFMA32(a, b, c) __builtin_amdgcn_mfma_f32_32x32x16_bf16((a), (b), (c), 0, 0, 0)
; template <bool CAUSAL>
; __device__ __forceinline__ void attn_tile(const LAS unsigned char* Ks, const LAS unsigned char* Vts, const bf16x8 (&qf)[8], int qi, int r32, int hi, f32x16 (&O)[4], float& m2, float& l) {
;     ...
; #pragma unroll
;     for (int d = 0; d < 4; ++d)
; #pragma unroll
;         for (int r = 0; r < 16; ++r) O[d][r] = 0.f;
; #pragma unroll 1
;     for (int hf = 0; hf < 2; ++hf) {
;         f32x16 S[4];
; #pragma unroll
;         for (int s = 0; s < 4; ++s) {
;             f32x16 a;
; #pragma unroll
;             for (int r = 0; r < 16; ++r) a[r] = 0.f;
;             const LAS unsigned char* kp = Ks + (128 * hf + 32 * s + r32) * KS_STRIDE + 16 * hi;
; #pragma unroll
;             for (int d0 = 0; d0 < 8; ++d0) { const bf16x8 kf = *(const LAS bf16x8*)(kp + 32 * d0); a = MFMA32(kf, qf[d0], a); }
; __device__ __forceinline__ void stage_kv_store(LAS unsigned char* lds, const u32x4 (&kr)[8], const u32x4 (&vr)[8], int tid) {
; #pragma unroll
;     for (int i = 0; i < 8; ++i) { const int c = tid + 512 * i, row = c >> 4, ch = c & 15; *(LAS u32x4*)(lds + LDS_KS + row * KS_STRIDE + ch * 16) = kr[i]; }
; #pragma unroll
;     for (int i = 0; i < 8; ++i) { const int c = tid + 512 * i, row = c >> 5, ch = c & 31; *(LAS u32x4*)(lds + LDS_VT + row * VT_STRIDE + ch * 16) = vr[i]; }
	ds_write_b128 v88, v[2:5]
	ds_write_b128 v90, v[6:9]
	ds_write_b128 v92, v[10:13]
	ds_write_b128 v94, v[14:17]
	ds_write_b128 v96, v[18:21]
	ds_write_b128 v98, v[22:25]
	ds_write_b128 v100, v[26:29]
	ds_write_b128 v66, v[30:33]
	ds_write_b128 v70, v[34:37]
	ds_write_b128 v72, v[38:41]
	ds_write_b128 v74, v[42:45]
	v_mov_b32_e32 v32, 0
	ds_write_b128 v0, v[46:49]
	v_mad_u64_u32 v[0:1], s[16:17], v78, s20, v[68:69]
	ds_write_b128 v0, v[50:53]
	v_mad_u64_u32 v[0:1], s[16:17], v80, s20, v[68:69]
	ds_write_b128 v0, v[54:57]
	v_mad_u64_u32 v[0:1], s[16:17], v82, s20, v[68:69]
	ds_write_b128 v0, v[58:61]
	v_mad_u64_u32 v[0:1], s[16:17], v84, s20, v[68:69]
	ds_write_b128 v0, v[62:65]
	v_mul_u32_u24_e32 v0, 0x210, v163
	v_add3_u32 v170, s19, v164, v0
	v_mov_b32_e32 v48, 0
	v_mov_b32_e32 v49, v171
	v_mov_b32_e32 v50, v171
	v_mov_b32_e32 v51, v171
	v_mov_b32_e32 v52, v171
	v_mov_b32_e32 v53, v171
	v_mov_b32_e32 v54, v171
	v_mov_b32_e32 v55, v171
	v_mov_b32_e32 v56, v171
	v_mov_b32_e32 v57, v171
	v_mov_b32_e32 v58, v171
	v_mov_b32_e32 v59, v171
	v_mov_b32_e32 v60, v171
	v_mov_b32_e32 v61, v171
	v_mov_b32_e32 v62, v171
	v_mov_b32_e32 v63, v171
	v_mov_b32_e32 v33, v171
	v_mov_b32_e32 v34, v171
	v_mov_b32_e32 v35, v171
	v_mov_b32_e32 v36, v171
	v_mov_b32_e32 v37, v171
	v_mov_b32_e32 v38, v171
	v_mov_b32_e32 v39, v171
	v_mov_b32_e32 v40, v171
	v_mov_b32_e32 v41, v171
	v_mov_b32_e32 v42, v171
	v_mov_b32_e32 v43, v171
	v_mov_b32_e32 v44, v171
	v_mov_b32_e32 v45, v171
	v_mov_b32_e32 v46, v171
	v_mov_b32_e32 v47, v171
	v_mov_b32_e32 v16, 0
	v_mov_b32_e32 v17, v171
	v_mov_b32_e32 v18, v171
	v_mov_b32_e32 v19, v171
	v_mov_b32_e32 v20, v171
	v_mov_b32_e32 v21, v171
	v_mov_b32_e32 v22, v171
	v_mov_b32_e32 v23, v171
	v_mov_b32_e32 v24, v171
	v_mov_b32_e32 v25, v171
	v_mov_b32_e32 v26, v171
	v_mov_b32_e32 v27, v171
	v_mov_b32_e32 v28, v171
	v_mov_b32_e32 v29, v171
	v_mov_b32_e32 v30, v171
	v_mov_b32_e32 v31, v171
	v_mov_b32_e32 v0, 0
	v_mov_b32_e32 v1, v171
	v_mov_b32_e32 v2, v171
	v_mov_b32_e32 v3, v171
	v_mov_b32_e32 v4, v171
	v_mov_b32_e32 v5, v171
	v_mov_b32_e32 v6, v171
	v_mov_b32_e32 v7, v171
	v_mov_b32_e32 v8, v171
	v_mov_b32_e32 v9, v171
	v_mov_b32_e32 v10, v171
	v_mov_b32_e32 v11, v171
	v_mov_b32_e32 v12, v171
	v_mov_b32_e32 v13, v171
	v_mov_b32_e32 v14, v171
	v_mov_b32_e32 v15, v171
	s_waitcnt lgkmcnt(0)
	s_barrier
.LBB0_52:
	v_lshl_or_b32 v64, s15, 7, v163
	v_mad_u32_u24 v176, v64, s86, v169
	ds_read_b128 v[200:203], v176
	ds_read_b128 v[204:207], v176 offset:32
	ds_read_b128 v[208:211], v176 offset:64
	ds_read_b128 v[212:215], v176 offset:96
	ds_read_b128 v[216:219], v176 offset:128
	ds_read_b128 v[220:223], v176 offset:160
	ds_read_b128 v[224:227], v176 offset:192
	ds_read_b128 v[228:231], v176 offset:224
	v_mov_b32_e32 v177, v162
	s_waitcnt vmcnt(0) lgkmcnt(7)
	v_mfma_f32_32x32x16_bf16 v[112:127], v[200:203], v[130:133], 0
	ds_read_b128 v[200:203], v176 offset:8704
	s_waitcnt lgkmcnt(7)
	v_mfma_f32_32x32x16_bf16 v[112:127], v[204:207], v[134:137], v[112:127]
	ds_read_b128 v[204:207], v176 offset:8736
	s_waitcnt lgkmcnt(7)
	v_mfma_f32_32x32x16_bf16 v[112:127], v[208:211], v[138:141], v[112:127]
	ds_read_b128 v[208:211], v176 offset:8768
	s_waitcnt lgkmcnt(7)
	v_mfma_f32_32x32x16_bf16 v[112:127], v[212:215], v[142:145], v[112:127]
	ds_read_b128 v[212:215], v176 offset:8800
	s_waitcnt lgkmcnt(7)
	v_mfma_f32_32x32x16_bf16 v[112:127], v[216:219], v[146:149], v[112:127]
	ds_read_b128 v[216:219], v176 offset:8832
	s_waitcnt lgkmcnt(7)
	v_mfma_f32_32x32x16_bf16 v[112:127], v[220:223], v[150:153], v[112:127]
	ds_read_b128 v[220:223], v176 offset:8864
	s_waitcnt lgkmcnt(7)
	v_mfma_f32_32x32x16_bf16 v[112:127], v[224:227], v[154:157], v[112:127]
	ds_read_b128 v[224:227], v176 offset:8896
	s_waitcnt lgkmcnt(7)
	v_mfma_f32_32x32x16_bf16 v[112:127], v[228:231], v[158:161], v[112:127]
	ds_read_b128 v[228:231], v176 offset:8928
	s_waitcnt lgkmcnt(7)
	v_mfma_f32_32x32x16_bf16 v[96:111], v[200:203], v[130:133], 0
	ds_read_b128 v[200:203], v176 offset:17408
	s_waitcnt lgkmcnt(7)
	v_mfma_f32_32x32x16_bf16 v[96:111], v[204:207], v[134:137], v[96:111]
	ds_read_b128 v[204:207], v176 offset:17440
	s_waitcnt lgkmcnt(7)
	v_mfma_f32_32x32x16_bf16 v[96:111], v[208:211], v[138:141], v[96:111]
	ds_read_b128 v[208:211], v176 offset:17472
	s_waitcnt lgkmcnt(7)
	v_mfma_f32_32x32x16_bf16 v[96:111], v[212:215], v[142:145], v[96:111]
	ds_read_b128 v[212:215], v176 offset:17504
	s_waitcnt lgkmcnt(7)
	v_mfma_f32_32x32x16_bf16 v[96:111], v[216:219], v[146:149], v[96:111]
	ds_read_b128 v[216:219], v176 offset:17536
	s_waitcnt lgkmcnt(7)
	v_mfma_f32_32x32x16_bf16 v[96:111], v[220:223], v[150:153], v[96:111]
	ds_read_b128 v[220:223], v176 offset:17568
	s_waitcnt lgkmcnt(7)
	v_mfma_f32_32x32x16_bf16 v[96:111], v[224:227], v[154:157], v[96:111]
	ds_read_b128 v[224:227], v176 offset:17600
	s_waitcnt lgkmcnt(7)
	v_mfma_f32_32x32x16_bf16 v[96:111], v[228:231], v[158:161], v[96:111]
	ds_read_b128 v[228:231], v176 offset:17632
	s_waitcnt lgkmcnt(7)
	v_mfma_f32_32x32x16_bf16 v[64:79], v[200:203], v[130:133], 0
	ds_read_b128 v[200:203], v176 offset:26112
	s_waitcnt lgkmcnt(7)
	v_mfma_f32_32x32x16_bf16 v[64:79], v[204:207], v[134:137], v[64:79]
	ds_read_b128 v[204:207], v176 offset:26144
	s_waitcnt lgkmcnt(7)
	v_mfma_f32_32x32x16_bf16 v[64:79], v[208:211], v[138:141], v[64:79]
	ds_read_b128 v[208:211], v176 offset:26176
	s_waitcnt lgkmcnt(7)
	v_mfma_f32_32x32x16_bf16 v[64:79], v[212:215], v[142:145], v[64:79]
	ds_read_b128 v[212:215], v176 offset:26208
	s_waitcnt lgkmcnt(7)
	v_mfma_f32_32x32x16_bf16 v[64:79], v[216:219], v[146:149], v[64:79]
	ds_read_b128 v[216:219], v176 offset:26240
	s_waitcnt lgkmcnt(7)
; #define LAS __attribute__((address_space(3)))
; __device__ __forceinline__ int crow(int r, int hi) { return (r & 3) + 8 * (r >> 2) + 4 * hi; }
; #define MFMA32(a, b, c) __builtin_amdgcn_mfma_f32_32x32x16_bf16((a), (b), (c), 0, 0, 0)
; template <bool CAUSAL>
; __device__ __forceinline__ void attn_tile(const LAS unsigned char* Ks, const LAS unsigned char* Vts, const bf16x8 (&qf)[8], int qi, int r32, int hi, f32x16 (&O)[4], float& m2, float& l) {
;     ...
;             for (int d0 = 0; d0 < 8; ++d0) { const bf16x8 kf = *(const LAS bf16x8*)(kp + 32 * d0); a = MFMA32(kf, qf[d0], a); }
;             S[s] = a;
;             __builtin_amdgcn_sched_barrier(0);
;         }
;         float mx = -1.0e30f;
; #pragma unroll
;         for (int s = 0; s < 4; ++s)
; #pragma unroll
;             for (int r = 0; r < 16; ++r) { float v = S[s][r]; if (CAUSAL) { if (128 * hf + 32 * s + crow(r, hi) > qi) v = -INFINITY; S[s][r] = v; } mx = fmaxf(mx, v); }
;         mx = fmaxf(mx, __shfl_xor(mx, 32));
;         const float mn = fmaxf(m, mx * c), alpha = __builtin_amdgcn_exp2f(m - mn);
;         m = mn; lsum *= alpha;
; #pragma unroll
;         for (int d = 0; d < 4; ++d)
; #pragma unroll
;             for (int r = 0; r < 16; ++r) O[d][r] *= alpha;
	v_mfma_f32_32x32x16_bf16 v[64:79], v[220:223], v[150:153], v[64:79]
	ds_read_b128 v[220:223], v176 offset:26272
	s_waitcnt lgkmcnt(7)
	v_mfma_f32_32x32x16_bf16 v[64:79], v[224:227], v[154:157], v[64:79]
	ds_read_b128 v[224:227], v176 offset:26304
	s_waitcnt lgkmcnt(7)
	v_mfma_f32_32x32x16_bf16 v[64:79], v[228:231], v[158:161], v[64:79]
	ds_read_b128 v[228:231], v176 offset:26336
	s_waitcnt lgkmcnt(7)
	v_mfma_f32_32x32x16_bf16 v[80:95], v[200:203], v[130:133], 0
	s_waitcnt lgkmcnt(6)
	v_mfma_f32_32x32x16_bf16 v[80:95], v[204:207], v[134:137], v[80:95]
	s_waitcnt lgkmcnt(5)
	v_mfma_f32_32x32x16_bf16 v[80:95], v[208:211], v[138:141], v[80:95]
	s_waitcnt lgkmcnt(4)
	v_mfma_f32_32x32x16_bf16 v[80:95], v[212:215], v[142:145], v[80:95]
	s_waitcnt lgkmcnt(3)
	v_mfma_f32_32x32x16_bf16 v[80:95], v[216:219], v[146:149], v[80:95]
	s_waitcnt lgkmcnt(2)
	v_mfma_f32_32x32x16_bf16 v[80:95], v[220:223], v[150:153], v[80:95]
	s_waitcnt lgkmcnt(1)
	v_mfma_f32_32x32x16_bf16 v[80:95], v[224:227], v[154:157], v[80:95]
	s_waitcnt lgkmcnt(0)
	v_mfma_f32_32x32x16_bf16 v[80:95], v[228:231], v[158:161], v[80:95]
	v_max3_f32 v162, v112, s69, v113
	v_max3_f32 v162, v162, v114, v115
	v_max3_f32 v162, v162, v116, v117
	v_max3_f32 v162, v162, v118, v119
	v_max3_f32 v162, v162, v120, v121
	v_max3_f32 v162, v162, v122, v123
	v_max3_f32 v162, v162, v124, v125
	v_max3_f32 v162, v162, v126, v127
	v_max3_f32 v162, v162, v96, v97
	v_max3_f32 v162, v162, v98, v99
	v_max3_f32 v162, v162, v100, v101
	v_max3_f32 v162, v162, v102, v103
	v_max3_f32 v162, v162, v104, v105
	v_max3_f32 v162, v162, v106, v107
	v_max3_f32 v162, v162, v108, v109
	v_max3_f32 v162, v162, v110, v111
	v_max3_f32 v162, v162, v64, v65
	v_max3_f32 v162, v162, v66, v67
	v_max3_f32 v162, v162, v68, v69
	v_max3_f32 v162, v162, v70, v71
	v_max3_f32 v162, v162, v72, v73
	v_max3_f32 v162, v162, v74, v75
	v_max3_f32 v162, v162, v76, v77
	v_max3_f32 v162, v162, v78, v79
	v_max3_f32 v162, v162, v80, v81
	v_max3_f32 v162, v162, v82, v83
	v_max3_f32 v162, v162, v84, v85
	v_max3_f32 v162, v162, v86, v87
	v_max3_f32 v162, v162, v88, v89
	v_max3_f32 v162, v162, v90, v91
	v_max3_f32 v162, v162, v92, v93
	v_max3_f32 v162, v162, v94, v95
	ds_bpermute_b32 v172, v166, v162
	s_waitcnt lgkmcnt(0)
	v_max_f32_e32 v172, v172, v172
	v_max_f32_e32 v162, v162, v172
	v_mul_f32_e32 v162, 0x3e0293ee, v162
	v_max_f32_e32 v172, v177, v177
	v_max_f32_e32 v162, v172, v162
	v_sub_f32_e32 v172, v177, v162
	v_fma_f32 v112, v112, s87, -v162
	v_exp_f32_e32 v172, v172
	v_exp_f32_e32 v181, v112
	v_fma_f32 v113, v113, s87, -v162
	v_exp_f32_e32 v182, v113
	v_fma_f32 v113, v114, s87, -v162
	v_exp_f32_e32 v183, v113
	v_fma_f32 v113, v115, s87, -v162
	v_exp_f32_e32 v184, v113
	v_fma_f32 v113, v116, s87, -v162
	v_fma_f32 v112, v171, v172, v181
	v_exp_f32_e32 v185, v113
	v_fma_f32 v113, v117, s87, -v162
	v_add_f32_e32 v112, v182, v112
	v_exp_f32_e32 v186, v113
	v_fma_f32 v113, v118, s87, -v162
	v_add_f32_e32 v112, v183, v112
	v_exp_f32_e32 v187, v113
	v_fma_f32 v113, v119, s87, -v162
	v_add_f32_e32 v112, v184, v112
	v_exp_f32_e32 v188, v113
	v_fma_f32 v113, v120, s87, -v162
	v_add_f32_e32 v112, v185, v112
	v_exp_f32_e32 v113, v113
	v_fma_f32 v114, v121, s87, -v162
	v_add_f32_e32 v112, v186, v112
	v_exp_f32_e32 v116, v114
	v_fma_f32 v114, v122, s87, -v162
	v_add_f32_e32 v112, v187, v112
	v_exp_f32_e32 v119, v114
	v_fma_f32 v114, v123, s87, -v162
	v_add_f32_e32 v112, v188, v112
	v_exp_f32_e32 v121, v114
	v_fma_f32 v114, v124, s87, -v162
	v_add_f32_e32 v112, v113, v112
	v_exp_f32_e32 v171, v114
	v_fma_f32 v114, v125, s87, -v162
	v_add_f32_e32 v112, v116, v112
	v_exp_f32_e32 v175, v114
	v_fma_f32 v114, v126, s87, -v162
	v_add_f32_e32 v112, v119, v112
	v_exp_f32_e32 v178, v114
	v_fma_f32 v114, v127, s87, -v162
	v_add_f32_e32 v112, v121, v112
	v_exp_f32_e32 v180, v114
	v_add_f32_e32 v112, v171, v112
	v_add_f32_e32 v112, v175, v112
	v_add_f32_e32 v112, v178, v112
	v_fma_f32 v96, v96, s87, -v162
	v_add_f32_e32 v114, v180, v112
	v_exp_f32_e32 v112, v96
	v_fma_f32 v97, v97, s87, -v162
	v_pk_mul_f32 v[62:63], v[62:63], v[172:173] op_sel_hi:[1,0]
	v_pk_mul_f32 v[60:61], v[60:61], v[172:173] op_sel_hi:[1,0]
	v_add_f32_e32 v96, v112, v114
	v_exp_f32_e32 v114, v97
	v_fma_f32 v97, v98, s87, -v162
	v_exp_f32_e32 v117, v97
	v_fma_f32 v97, v99, s87, -v162
	v_exp_f32_e32 v120, v97
	v_fma_f32 v97, v100, s87, -v162
	v_exp_f32_e32 v124, v97
	v_fma_f32 v97, v101, s87, -v162
	v_pk_mul_f32 v[58:59], v[58:59], v[172:173] op_sel_hi:[1,0]
	v_pk_mul_f32 v[56:57], v[56:57], v[172:173] op_sel_hi:[1,0]
	v_pk_mul_f32 v[54:55], v[54:55], v[172:173] op_sel_hi:[1,0]
	v_pk_mul_f32 v[52:53], v[52:53], v[172:173] op_sel_hi:[1,0]
	v_pk_mul_f32 v[50:51], v[50:51], v[172:173] op_sel_hi:[1,0]
	v_pk_mul_f32 v[48:49], v[48:49], v[172:173] op_sel_hi:[1,0]
	v_pk_mul_f32 v[46:47], v[46:47], v[172:173] op_sel_hi:[1,0]
	v_pk_mul_f32 v[44:45], v[44:45], v[172:173] op_sel_hi:[1,0]
	v_pk_mul_f32 v[42:43], v[42:43], v[172:173] op_sel_hi:[1,0]
	v_pk_mul_f32 v[40:41], v[40:41], v[172:173] op_sel_hi:[1,0]
	v_pk_mul_f32 v[38:39], v[38:39], v[172:173] op_sel_hi:[1,0]
	v_pk_mul_f32 v[36:37], v[36:37], v[172:173] op_sel_hi:[1,0]
	v_pk_mul_f32 v[34:35], v[34:35], v[172:173] op_sel_hi:[1,0]
	v_pk_mul_f32 v[32:33], v[32:33], v[172:173] op_sel_hi:[1,0]
	v_pk_mul_f32 v[30:31], v[30:31], v[172:173] op_sel_hi:[1,0]
	v_pk_mul_f32 v[28:29], v[28:29], v[172:173] op_sel_hi:[1,0]
	v_pk_mul_f32 v[26:27], v[26:27], v[172:173] op_sel_hi:[1,0]
	v_pk_mul_f32 v[24:25], v[24:25], v[172:173] op_sel_hi:[1,0]
	v_pk_mul_f32 v[22:23], v[22:23], v[172:173] op_sel_hi:[1,0]
	v_pk_mul_f32 v[20:21], v[20:21], v[172:173] op_sel_hi:[1,0]
; #define LAS __attribute__((address_space(3)))
; __device__ __forceinline__ unsigned cvtpk(float lo, float hi) { f32x2 v = {lo, hi}; bf16x2_t b = __builtin_convertvector(v, bf16x2_t); return __builtin_bit_cast(unsigned, b); }
; #define MFMA32(a, b, c) __builtin_amdgcn_mfma_f32_32x32x16_bf16((a), (b), (c), 0, 0, 0)
; template <bool CAUSAL>
; __device__ __forceinline__ void attn_tile(const LAS unsigned char* Ks, const LAS unsigned char* Vts, const bf16x8 (&qf)[8], int qi, int r32, int hi, f32x16 (&O)[4], float& m2, float& l) {
;     ...
;             for (int r = 0; r < 16; ++r) O[d][r] *= alpha;
; #pragma unroll
;         for (int s = 0; s < 4; ++s)
; #pragma unroll
;             for (int r = 0; r < 16; ++r) { const float p = __builtin_amdgcn_exp2f(S[s][r] * c - mn); S[s][r] = p; lsum += p; }
; #pragma unroll
;         for (int s = 0; s < 4; ++s)
; #pragma unroll
;             for (int j = 0; j < 2; ++j) {
;                 u32x4 pw; pw.x = cvtpk(S[s][8 * j + 0], S[s][8 * j + 1]); pw.y = cvtpk(S[s][8 * j + 2], S[s][8 * j + 3]); pw.z = cvtpk(S[s][8 * j + 4], S[s][8 * j + 5]); pw.w = cvtpk(S[s][8 * j + 6], S[s][8 * j + 7]);
;                 const bf16x8 pf = __builtin_bit_cast(bf16x8, pw);
; #pragma unroll
;                 for (int d = 0; d < 4; ++d) {
;                     const LAS unsigned char* vp = Vts + (32 * d + r32) * VT_STRIDE + (128 * hf + 32 * s + 16 * j + 4 * hi) * 2;
;                     const s16x4 lo = *(const LAS s16x4*)vp, h4 = *(const LAS s16x4*)(vp + 16);
;                     const bf16x8 vf = __builtin_shufflevector(lo, h4, 0, 1, 2, 3, 4, 5, 6, 7);
;                     O[d] = MFMA32(vf, pf, O[d]);
;                 }
	v_pk_mul_f32 v[18:19], v[18:19], v[172:173] op_sel_hi:[1,0]
	v_pk_mul_f32 v[16:17], v[16:17], v[172:173] op_sel_hi:[1,0]
	v_pk_mul_f32 v[14:15], v[14:15], v[172:173] op_sel_hi:[1,0]
	v_pk_mul_f32 v[12:13], v[12:13], v[172:173] op_sel_hi:[1,0]
	v_pk_mul_f32 v[10:11], v[10:11], v[172:173] op_sel_hi:[1,0]
	v_pk_mul_f32 v[8:9], v[8:9], v[172:173] op_sel_hi:[1,0]
	v_pk_mul_f32 v[6:7], v[6:7], v[172:173] op_sel_hi:[1,0]
	v_pk_mul_f32 v[4:5], v[4:5], v[172:173] op_sel_hi:[1,0]
	v_pk_mul_f32 v[2:3], v[2:3], v[172:173] op_sel_hi:[1,0]
	v_pk_mul_f32 v[0:1], v[0:1], v[172:173] op_sel_hi:[1,0]
	v_add_f32_e32 v96, v114, v96
	v_exp_f32_e32 v172, v97
	v_fma_f32 v97, v102, s87, -v162
	v_add_f32_e32 v96, v117, v96
	v_exp_f32_e32 v176, v97
	v_fma_f32 v97, v103, s87, -v162
	v_add_f32_e32 v96, v120, v96
	v_exp_f32_e32 v179, v97
	v_fma_f32 v97, v104, s87, -v162
	v_add_f32_e32 v96, v124, v96
	v_exp_f32_e32 v101, v97
	v_fma_f32 v97, v105, s87, -v162
	v_add_f32_e32 v96, v172, v96
	v_exp_f32_e32 v104, v97
	v_fma_f32 v97, v106, s87, -v162
	v_add_f32_e32 v96, v176, v96
	v_exp_f32_e32 v115, v97
	v_fma_f32 v97, v107, s87, -v162
	v_add_f32_e32 v96, v179, v96
	v_exp_f32_e32 v118, v97
	v_fma_f32 v97, v108, s87, -v162
	v_add_f32_e32 v96, v101, v96
	v_exp_f32_e32 v122, v97
	v_fma_f32 v97, v109, s87, -v162
	v_add_f32_e32 v96, v104, v96
	v_exp_f32_e32 v125, v97
	v_fma_f32 v97, v110, s87, -v162
	v_add_f32_e32 v96, v115, v96
	v_exp_f32_e32 v173, v97
	v_fma_f32 v97, v111, s87, -v162
	v_add_f32_e32 v96, v118, v96
	v_exp_f32_e32 v177, v97
	v_fma_f32 v64, v64, s87, -v162
	v_add_f32_e32 v96, v122, v96
	v_exp_f32_e32 v99, v64
	v_fma_f32 v65, v65, s87, -v162
	v_add_f32_e32 v96, v125, v96
	v_exp_f32_e32 v102, v65
	v_fma_f32 v65, v66, s87, -v162
	v_add_f32_e32 v96, v173, v96
	v_exp_f32_e32 v105, v65
	v_fma_f32 v65, v67, s87, -v162
	v_add_f32_e32 v96, v177, v96
	v_exp_f32_e32 v107, v65
	v_fma_f32 v65, v68, s87, -v162
	v_add_f32_e32 v64, v99, v96
	v_exp_f32_e32 v109, v65
	v_fma_f32 v65, v69, s87, -v162
	v_add_f32_e32 v64, v102, v64
	v_exp_f32_e32 v111, v65
	v_fma_f32 v65, v70, s87, -v162
	v_add_f32_e32 v64, v105, v64
	v_exp_f32_e32 v126, v65
	v_fma_f32 v65, v71, s87, -v162
	v_add_f32_e32 v64, v107, v64
	v_exp_f32_e32 v174, v65
	v_fma_f32 v65, v72, s87, -v162
	v_add_f32_e32 v64, v109, v64
	v_exp_f32_e32 v98, v65
	v_fma_f32 v65, v73, s87, -v162
	v_add_f32_e32 v64, v111, v64
	v_exp_f32_e32 v100, v65
	v_fma_f32 v65, v74, s87, -v162
	v_add_f32_e32 v64, v126, v64
	v_exp_f32_e32 v103, v65
	v_fma_f32 v65, v75, s87, -v162
	v_add_f32_e32 v64, v174, v64
	v_exp_f32_e32 v106, v65
	v_fma_f32 v65, v76, s87, -v162
	v_add_f32_e32 v64, v98, v64
	v_exp_f32_e32 v108, v65
	v_fma_f32 v65, v77, s87, -v162
	v_add_f32_e32 v64, v100, v64
	v_exp_f32_e32 v110, v65
	v_fma_f32 v65, v78, s87, -v162
	v_add_f32_e32 v64, v103, v64
	v_exp_f32_e32 v123, v65
	v_fma_f32 v65, v79, s87, -v162
	v_add_f32_e32 v64, v106, v64
	v_exp_f32_e32 v127, v65
	v_add_f32_e32 v64, v108, v64
	v_add_f32_e32 v64, v110, v64
	v_add_f32_e32 v64, v123, v64
	v_add_f32_e32 v96, v127, v64
	v_fma_f32 v64, v80, s87, -v162
	v_exp_f32_e32 v97, v64
	v_fma_f32 v64, v81, s87, -v162
	v_exp_f32_e32 v68, v64
	v_fma_f32 v64, v82, s87, -v162
	v_exp_f32_e32 v69, v64
	v_fma_f32 v64, v83, s87, -v162
	v_exp_f32_e32 v70, v64
	v_fma_f32 v64, v84, s87, -v162
	v_exp_f32_e32 v71, v64
	v_fma_f32 v64, v85, s87, -v162
	v_exp_f32_e32 v72, v64
	v_fma_f32 v64, v86, s87, -v162
	v_exp_f32_e32 v73, v64
	v_fma_f32 v64, v87, s87, -v162
	v_lshl_add_u32 v83, s15, 8, v170
	v_exp_f32_e32 v74, v64
	v_fma_f32 v64, v88, s87, -v162
	v_add_u32_e32 v84, 0x4000, v83
	v_add_u32_e32 v85, 0x8000, v83
	v_add_u32_e32 v86, 0xc000, v83
	ds_read_b64 v[200:201], v83
	ds_read_b64 v[202:203], v83 offset:16
	ds_read_b64 v[204:205], v84 offset:512
	ds_read_b64 v[206:207], v84 offset:528
	ds_read_b64 v[208:209], v85 offset:1024
	ds_read_b64 v[210:211], v85 offset:1040
	ds_read_b64 v[212:213], v86 offset:1536
	ds_read_b64 v[214:215], v86 offset:1552
	ds_read_b64 v[216:217], v83 offset:32
	ds_read_b64 v[218:219], v83 offset:48
	ds_read_b64 v[220:221], v84 offset:544
	ds_read_b64 v[222:223], v84 offset:560
	ds_read_b64 v[224:225], v85 offset:1056
	ds_read_b64 v[226:227], v85 offset:1072
	ds_read_b64 v[228:229], v86 offset:1568
	ds_read_b64 v[230:231], v86 offset:1584
	v_exp_f32_e32 v75, v64
	v_fma_f32 v64, v89, s87, -v162
	v_exp_f32_e32 v76, v64
	v_fma_f32 v64, v90, s87, -v162
	v_exp_f32_e32 v77, v64
	v_fma_f32 v64, v91, s87, -v162
	v_exp_f32_e32 v78, v64
	v_fma_f32 v64, v92, s87, -v162
	v_exp_f32_e32 v79, v64
	v_fma_f32 v64, v93, s87, -v162
	v_exp_f32_e32 v80, v64
	v_fma_f32 v64, v94, s87, -v162
	v_exp_f32_e32 v81, v64
	v_fma_f32 v64, v95, s87, -v162
	v_exp_f32_e32 v82, v64
	v_cvt_pk_bf16_f32 v64, v181, v182
	v_cvt_pk_bf16_f32 v65, v183, v184
	v_cvt_pk_bf16_f32 v66, v185, v186
	v_cvt_pk_bf16_f32 v67, v187, v188
	s_waitcnt lgkmcnt(14)
	s_nop 0
	v_mfma_f32_32x32x16_bf16 v[48:63], v[200:203], v[64:67], v[48:63]
	ds_read_b64 v[200:201], v83 offset:64
	ds_read_b64 v[202:203], v83 offset:80
	s_waitcnt lgkmcnt(14)
	v_mfma_f32_32x32x16_bf16 v[32:47], v[204:207], v[64:67], v[32:47]
	ds_read_b64 v[204:205], v84 offset:576
	ds_read_b64 v[206:207], v84 offset:592
	s_waitcnt lgkmcnt(14)
	v_mfma_f32_32x32x16_bf16 v[16:31], v[208:211], v[64:67], v[16:31]
	ds_read_b64 v[208:209], v85 offset:1088
	ds_read_b64 v[210:211], v85 offset:1104
	s_waitcnt lgkmcnt(14)
	v_mfma_f32_32x32x16_bf16 v[0:15], v[212:215], v[64:67], v[0:15]
	ds_read_b64 v[212:213], v86 offset:1600
	ds_read_b64 v[214:215], v86 offset:1616
	v_cvt_pk_bf16_f32 v64, v113, v116
	v_cvt_pk_bf16_f32 v65, v119, v121
	v_cvt_pk_bf16_f32 v66, v171, v175
	v_cvt_pk_bf16_f32 v67, v178, v180
	s_waitcnt lgkmcnt(14)
; #define LAS __attribute__((address_space(3)))
; __device__ __forceinline__ unsigned cvtpk(float lo, float hi) { f32x2 v = {lo, hi}; bf16x2_t b = __builtin_convertvector(v, bf16x2_t); return __builtin_bit_cast(unsigned, b); }
; #define MFMA32(a, b, c) __builtin_amdgcn_mfma_f32_32x32x16_bf16((a), (b), (c), 0, 0, 0)
; template <bool CAUSAL>
; __device__ __forceinline__ void attn_tile(const LAS unsigned char* Ks, const LAS unsigned char* Vts, const bf16x8 (&qf)[8], int qi, int r32, int hi, f32x16 (&O)[4], float& m2, float& l) {
;     ...
;         for (int s = 0; s < 4; ++s)
; #pragma unroll
;             for (int j = 0; j < 2; ++j) {
;                 u32x4 pw; pw.x = cvtpk(S[s][8 * j + 0], S[s][8 * j + 1]); pw.y = cvtpk(S[s][8 * j + 2], S[s][8 * j + 3]); pw.z = cvtpk(S[s][8 * j + 4], S[s][8 * j + 5]); pw.w = cvtpk(S[s][8 * j + 6], S[s][8 * j + 7]);
;                 const bf16x8 pf = __builtin_bit_cast(bf16x8, pw);
; #pragma unroll
;                 for (int d = 0; d < 4; ++d) {
;                     const LAS unsigned char* vp = Vts + (32 * d + r32) * VT_STRIDE + (128 * hf + 32 * s + 16 * j + 4 * hi) * 2;
;                     const s16x4 lo = *(const LAS s16x4*)vp, h4 = *(const LAS s16x4*)(vp + 16);
;                     const bf16x8 vf = __builtin_shufflevector(lo, h4, 0, 1, 2, 3, 4, 5, 6, 7);
;                     O[d] = MFMA32(vf, pf, O[d]);
;                 }
;                 __builtin_amdgcn_sched_barrier(0);
;             }
;     }
;     lsum += __shfl_xor(lsum, 32);
;     m2 = m; l = lsum;
; __device__ __forceinline__ void store_orow(bf16_t* orow, const f32x16 (&O)[4], float sc, int hi, bool st) {
; #pragma unroll
;     for (int d = 0; d < 4; ++d)
; #pragma unroll
;         for (int k = 0; k < 2; ++k) {
;             const unsigned x0 = cvtpk(O[d][8 * k + 0] * sc, O[d][8 * k + 1] * sc), x1 = cvtpk(O[d][8 * k + 2] * sc, O[d][8 * k + 3] * sc);
;             const unsigned y0 = cvtpk(O[d][8 * k + 4] * sc, O[d][8 * k + 5] * sc), y1 = cvtpk(O[d][8 * k + 6] * sc, O[d][8 * k + 7] * sc);
;             const auto r0 = __builtin_amdgcn_permlane32_swap(x0, y0, false, false), r1 = __builtin_amdgcn_permlane32_swap(x1, y1, false, false);
;             u32x4 w; w.x = r0[0]; w.y = r1[0]; w.z = r0[1]; w.w = r1[1];
;             if (st) *(u32x4*)(orow + 32 * d + 16 * k + 8 * hi) = w;
	s_nop 0
	v_mfma_f32_32x32x16_bf16 v[48:63], v[216:219], v[64:67], v[48:63]
	ds_read_b64 v[216:217], v83 offset:96
	ds_read_b64 v[218:219], v83 offset:112
	s_waitcnt lgkmcnt(14)
	v_mfma_f32_32x32x16_bf16 v[32:47], v[220:223], v[64:67], v[32:47]
	ds_read_b64 v[220:221], v84 offset:608
	ds_read_b64 v[222:223], v84 offset:624
	s_waitcnt lgkmcnt(14)
	v_mfma_f32_32x32x16_bf16 v[16:31], v[224:227], v[64:67], v[16:31]
	ds_read_b64 v[224:225], v85 offset:1120
	ds_read_b64 v[226:227], v85 offset:1136
	s_waitcnt lgkmcnt(14)
	v_mfma_f32_32x32x16_bf16 v[0:15], v[228:231], v[64:67], v[0:15]
	ds_read_b64 v[228:229], v86 offset:1632
	ds_read_b64 v[230:231], v86 offset:1648
	v_cvt_pk_bf16_f32 v64, v112, v114
	v_cvt_pk_bf16_f32 v65, v117, v120
	v_cvt_pk_bf16_f32 v66, v124, v172
	v_cvt_pk_bf16_f32 v67, v176, v179
	s_waitcnt lgkmcnt(14)
	s_nop 0
	v_mfma_f32_32x32x16_bf16 v[48:63], v[200:203], v[64:67], v[48:63]
	ds_read_b64 v[200:201], v83 offset:128
	ds_read_b64 v[202:203], v83 offset:144
	s_waitcnt lgkmcnt(14)
	v_mfma_f32_32x32x16_bf16 v[32:47], v[204:207], v[64:67], v[32:47]
	ds_read_b64 v[204:205], v84 offset:640
	ds_read_b64 v[206:207], v84 offset:656
	s_waitcnt lgkmcnt(14)
	v_mfma_f32_32x32x16_bf16 v[16:31], v[208:211], v[64:67], v[16:31]
	ds_read_b64 v[208:209], v85 offset:1152
	ds_read_b64 v[210:211], v85 offset:1168
	s_waitcnt lgkmcnt(14)
	v_mfma_f32_32x32x16_bf16 v[0:15], v[212:215], v[64:67], v[0:15]
	ds_read_b64 v[212:213], v86 offset:1664
	ds_read_b64 v[214:215], v86 offset:1680
	v_cvt_pk_bf16_f32 v64, v101, v104
	v_cvt_pk_bf16_f32 v65, v115, v118
	v_cvt_pk_bf16_f32 v66, v122, v125
	v_cvt_pk_bf16_f32 v67, v173, v177
	s_waitcnt lgkmcnt(14)
	s_nop 0
	v_mfma_f32_32x32x16_bf16 v[48:63], v[216:219], v[64:67], v[48:63]
	ds_read_b64 v[216:217], v83 offset:160
	ds_read_b64 v[218:219], v83 offset:176
	s_waitcnt lgkmcnt(14)
	v_mfma_f32_32x32x16_bf16 v[32:47], v[220:223], v[64:67], v[32:47]
	ds_read_b64 v[220:221], v84 offset:672
	ds_read_b64 v[222:223], v84 offset:688
	s_waitcnt lgkmcnt(14)
	v_mfma_f32_32x32x16_bf16 v[16:31], v[224:227], v[64:67], v[16:31]
	ds_read_b64 v[224:225], v85 offset:1184
	ds_read_b64 v[226:227], v85 offset:1200
	s_waitcnt lgkmcnt(14)
	v_mfma_f32_32x32x16_bf16 v[0:15], v[228:231], v[64:67], v[0:15]
	ds_read_b64 v[228:229], v86 offset:1696
	ds_read_b64 v[230:231], v86 offset:1712
	v_cvt_pk_bf16_f32 v64, v99, v102
	v_cvt_pk_bf16_f32 v65, v105, v107
	v_cvt_pk_bf16_f32 v66, v109, v111
	v_cvt_pk_bf16_f32 v67, v126, v174
	s_waitcnt lgkmcnt(14)
	s_nop 0
	v_mfma_f32_32x32x16_bf16 v[48:63], v[200:203], v[64:67], v[48:63]
	ds_read_b64 v[200:201], v83 offset:192
	ds_read_b64 v[202:203], v83 offset:208
	s_waitcnt lgkmcnt(14)
	v_mfma_f32_32x32x16_bf16 v[32:47], v[204:207], v[64:67], v[32:47]
	ds_read_b64 v[204:205], v84 offset:704
	ds_read_b64 v[206:207], v84 offset:720
	s_waitcnt lgkmcnt(14)
	v_mfma_f32_32x32x16_bf16 v[16:31], v[208:211], v[64:67], v[16:31]
	ds_read_b64 v[208:209], v85 offset:1216
	ds_read_b64 v[210:211], v85 offset:1232
	s_waitcnt lgkmcnt(14)
	v_mfma_f32_32x32x16_bf16 v[0:15], v[212:215], v[64:67], v[0:15]
	ds_read_b64 v[212:213], v86 offset:1728
	ds_read_b64 v[214:215], v86 offset:1744
	v_cvt_pk_bf16_f32 v64, v98, v100
	v_cvt_pk_bf16_f32 v65, v103, v106
	v_cvt_pk_bf16_f32 v66, v108, v110
	v_cvt_pk_bf16_f32 v67, v123, v127
	s_waitcnt lgkmcnt(14)
	s_nop 0
	v_mfma_f32_32x32x16_bf16 v[48:63], v[216:219], v[64:67], v[48:63]
	ds_read_b64 v[216:217], v83 offset:224
	ds_read_b64 v[218:219], v83 offset:240
	s_waitcnt lgkmcnt(14)
	v_mfma_f32_32x32x16_bf16 v[32:47], v[220:223], v[64:67], v[32:47]
	ds_read_b64 v[220:221], v84 offset:736
	ds_read_b64 v[222:223], v84 offset:752
	s_waitcnt lgkmcnt(14)
	v_mfma_f32_32x32x16_bf16 v[16:31], v[224:227], v[64:67], v[16:31]
	ds_read_b64 v[224:225], v85 offset:1248
	ds_read_b64 v[226:227], v85 offset:1264
	s_waitcnt lgkmcnt(14)
	v_mfma_f32_32x32x16_bf16 v[0:15], v[228:231], v[64:67], v[0:15]
	ds_read_b64 v[228:229], v86 offset:1760
	ds_read_b64 v[230:231], v86 offset:1776
	v_cvt_pk_bf16_f32 v88, v97, v68
	v_cvt_pk_bf16_f32 v89, v69, v70
	v_cvt_pk_bf16_f32 v90, v71, v72
	v_cvt_pk_bf16_f32 v91, v73, v74
	s_waitcnt lgkmcnt(14)
	s_nop 0
	v_mfma_f32_32x32x16_bf16 v[48:63], v[200:203], v[88:91], v[48:63]
	s_waitcnt lgkmcnt(12)
	v_mfma_f32_32x32x16_bf16 v[32:47], v[204:207], v[88:91], v[32:47]
	s_waitcnt lgkmcnt(10)
	v_mfma_f32_32x32x16_bf16 v[16:31], v[208:211], v[88:91], v[16:31]
	s_waitcnt lgkmcnt(8)
	v_mfma_f32_32x32x16_bf16 v[0:15], v[212:215], v[88:91], v[0:15]
	v_cvt_pk_bf16_f32 v88, v75, v76
	v_cvt_pk_bf16_f32 v89, v77, v78
	v_cvt_pk_bf16_f32 v90, v79, v80
	v_cvt_pk_bf16_f32 v91, v81, v82
	s_waitcnt lgkmcnt(6)
	s_nop 0
	v_mfma_f32_32x32x16_bf16 v[48:63], v[216:219], v[88:91], v[48:63]
	s_waitcnt lgkmcnt(4)
	v_mfma_f32_32x32x16_bf16 v[32:47], v[220:223], v[88:91], v[32:47]
	s_waitcnt lgkmcnt(2)
	v_mfma_f32_32x32x16_bf16 v[16:31], v[224:227], v[88:91], v[16:31]
	s_waitcnt lgkmcnt(0)
	v_mfma_f32_32x32x16_bf16 v[0:15], v[228:231], v[88:91], v[0:15]
	v_add_f32_e32 v64, v97, v96
	v_add_f32_e32 v64, v68, v64
	v_add_f32_e32 v64, v69, v64
	v_add_f32_e32 v64, v70, v64
	v_add_f32_e32 v64, v71, v64
	v_add_f32_e32 v64, v72, v64
	v_add_f32_e32 v64, v73, v64
	v_add_f32_e32 v64, v74, v64
	v_add_f32_e32 v64, v75, v64
	v_add_f32_e32 v64, v76, v64
	v_add_f32_e32 v64, v77, v64
	v_add_f32_e32 v64, v78, v64
	v_add_f32_e32 v64, v79, v64
	v_add_f32_e32 v64, v80, v64
	v_add_f32_e32 v64, v81, v64
	s_mov_b32 s15, 1
	s_and_b64 vcc, exec, s[60:61]
	s_mov_b64 s[60:61], 0
	v_add_f32_e32 v171, v82, v64
	s_cbranch_vccnz .LBB0_52
	ds_bpermute_b32 v65, v166, v171
	s_mov_b32 s29, s75
	s_lshl_b64 s[16:17], s[28:29], 14
	v_lshl_add_u64 v[66:67], s[16:17], 0, v[128:129]
	v_and_b32_e32 v64, 3, v168
	s_waitcnt lgkmcnt(0)
	v_add_f32_e32 v163, v171, v65
	v_div_scale_f32 v68, s[16:17], v163, v163, 1.0
	v_rcp_f32_e32 v69, v68
	v_mov_b32_e32 v65, v129
	v_mad_u64_u32 v[64:65], s[16:17], v66, 3, v[64:65]
	v_fma_f32 v70, -v68, v69, 1.0
	v_fmac_f32_e32 v69, v70, v69
	v_div_scale_f32 v70, vcc, 1.0, v163, 1.0
	v_mul_f32_e32 v71, v70, v69
	v_fma_f32 v72, -v68, v71, v70
	v_fmac_f32_e32 v71, v72, v69
	v_fma_f32 v68, -v68, v71, v70
	v_div_fmas_f32 v68, v68, v69, v71
	v_div_fixup_f32 v68, v68, v163, 1.0
	v_mad_u32_u24 v65, v67, 3, v65
	v_pk_mul_f32 v[48:49], v[48:49], v[68:69] op_sel_hi:[1,0]
	v_pk_mul_f32 v[50:51], v[50:51], v[68:69] op_sel_hi:[1,0]
	v_lshlrev_b64 v[66:67], 8, v[64:65]
	v_cvt_pk_bf16_f32 v48, v48, v49
	v_cvt_pk_bf16_f32 v49, v50, v51
	v_pk_mul_f32 v[50:51], v[52:53], v[68:69] op_sel_hi:[1,0]
	v_pk_mul_f32 v[52:53], v[54:55], v[68:69] op_sel_hi:[1,0]
	v_lshl_add_u64 v[66:67], s[0:1], 0, v[66:67]
	v_lshlrev_b32_e32 v128, 1, v164
	v_cvt_pk_bf16_f32 v50, v50, v51
	v_cvt_pk_bf16_f32 v51, v52, v53
	v_lshl_add_u64 v[66:67], v[66:67], 0, v[128:129]
	v_permlane32_swap_b32_e32 v48, v50
	v_permlane32_swap_b32_e32 v49, v51
	s_and_saveexec_b64 s[28:29], s[6:7]
	s_cbranch_execz .LBB0_55
	flat_store_dwordx4 v[66:67], v[48:51]
